# adds EpiDown (MLP-down GEMM) epilogue: all 16 residual (XB) loads hoisted to epilogue start into dead K-loop fragment registers, exact counted vmcnt waits (was 16x load->vmcnt(0)->2 stores)
# speedup vs baseline: 1.0095x; 1.0095x over previous
; __device__ __forceinline__ unsigned pk2(float lo, float hi) { f32x2 v = {lo, hi}; bf16x2_hw b = __builtin_convertvector(v, bf16x2_hw); return __builtin_bit_cast(unsigned, b); }
; __device__ __forceinline__ void st_bf8(bf16* p, f32x4 a, f32x4 b) { u32x4 w; w.x = pk2(a[0], a[1]); w.y = pk2(a[2], a[3]); w.z = pk2(b[0], b[1]); w.w = pk2(b[2], b[3]); *(u32x4*)p = w; }
; __device__ __forceinline__ void ld_bf8(const bf16* p, f32x4& a, f32x4& b) { const u32x4 w = *(const u32x4*)p; a = (f32x4){bflo(w.x), bfhi(w.x), bflo(w.y), bfhi(w.y)}; b = (f32x4){bflo(w.z), bfhi(w.z), bflo(w.w), bfhi(w.w)}; }
;     __device__ __forceinline__ void operator()(AccRef acc, const pg8::Unit& u, int wr, int wc, int fr, int fq) const {
;         const int c0 = u.pn * 256;
;         EPI_LOOP_P( if (row < nvalid) { f32x4 b0, b1; ld_bf8(XB + rw * 1024 + c0 + cl, b0, b1); float* p = y + rw * 1024 + c0 + cl; *(f32x4*)p = b0 + v0; *(f32x4*)(p + 4) = b1 + v1; } )
;     }
.LBB0_241:
	s_lshl_b32 s20, s47, 8
	s_ashr_i32 s21, s20, 31
	v_lshl_add_u32 v144, s48, 8, v137
	v_ashrrev_i32_e32 v145, 31, v144
	v_lshlrev_b64 v[148:149], 11, v[144:145]
	v_lshl_add_u64 v[148:149], s[12:13], 0, v[148:149]
	v_lshl_add_u64 v[148:149], s[20:21], 1, v[148:149]
	v_lshlrev_b32_e32 v184, 1, v136
	v_lshl_add_u64 v[148:149], v[148:149], 0, v[184:185]
	s_mov_b64 vcc, 0x8000
	s_mov_b64 s[22:23], 0x28000
	global_load_dwordx4 v[160:163], v[148:149], off
	global_load_dwordx4 v[164:167], v[148:149], off offset:256
	v_lshl_add_u64 v[148:149], v[148:149], 0, vcc
	global_load_dwordx4 v[168:171], v[148:149], off
	global_load_dwordx4 v[172:175], v[148:149], off offset:256
	v_lshl_add_u64 v[148:149], v[148:149], 0, vcc
	global_load_dwordx4 v[176:179], v[148:149], off
	global_load_dwordx4 v[180:183], v[148:149], off offset:256
	v_lshl_add_u64 v[148:149], v[148:149], 0, vcc
	global_load_dwordx4 v[190:193], v[148:149], off
	global_load_dwordx4 v[196:199], v[148:149], off offset:256
	v_lshl_add_u64 v[148:149], v[148:149], 0, s[22:23]
	global_load_dwordx4 v[200:203], v[148:149], off
	global_load_dwordx4 v[212:215], v[148:149], off offset:256
	v_lshl_add_u64 v[148:149], v[148:149], 0, vcc
	global_load_dwordx4 v[216:219], v[148:149], off
	global_load_dwordx4 v[220:223], v[148:149], off offset:256
	v_lshl_add_u64 v[148:149], v[148:149], 0, vcc
	global_load_dwordx4 v[224:227], v[148:149], off
	global_load_dwordx4 v[228:231], v[148:149], off offset:256
	v_lshl_add_u64 v[148:149], v[148:149], 0, vcc
	global_load_dwordx4 v[232:235], v[148:149], off
	global_load_dwordx4 v[236:239], v[148:149], off offset:256
	s_lshl_b32 s20, s47, 8
	v_lshl_add_u32 v144, s48, 8, v137
	s_ashr_i32 s21, s20, 31
	v_cmp_gt_i32_e32 vcc, s24, v144
	v_lshlrev_b32_e32 v184, 1, v136
	v_lshlrev_b32_e32 v142, 2, v136
	s_and_saveexec_b64 s[22:23], vcc
	s_cbranch_execz .LBB0_243
	v_ashrrev_i32_e32 v145, 31, v144
	v_lshlrev_b64 v[148:149], 11, v[144:145]
	v_lshl_add_u64 v[148:149], s[12:13], 0, v[148:149]
	v_lshl_add_u64 v[148:149], s[20:21], 1, v[148:149]
	v_lshl_add_u64 v[152:153], v[148:149], 0, v[184:185]
	v_lshlrev_b64 v[154:155], 12, v[144:145]
	v_lshl_add_u64 v[154:155], s[10:11], 0, v[154:155]
	v_mov_b32_e32 v143, v185
	v_lshl_add_u64 v[154:155], s[20:21], 2, v[154:155]
	v_lshl_add_u64 v[154:155], v[154:155], 0, v[142:143]
	s_waitcnt vmcnt(15)
	v_lshlrev_b32_e32 v156, 16, v160
	v_and_b32_e32 v157, 0xffff0000, v160
	v_lshlrev_b32_e32 v148, 16, v161
	v_and_b32_e32 v149, 0xffff0000, v161
	v_lshlrev_b32_e32 v158, 16, v162
	v_and_b32_e32 v159, 0xffff0000, v162
	v_lshlrev_b32_e32 v150, 16, v163
	v_and_b32_e32 v151, 0xffff0000, v163
	v_pk_add_f32 v[126:127], v[126:127], v[148:149]
	v_pk_add_f32 v[124:125], v[124:125], v[156:157]
	v_pk_add_f32 v[122:123], v[122:123], v[150:151]
	v_pk_add_f32 v[120:121], v[120:121], v[158:159]
	global_store_dwordx4 v[154:155], v[124:127], off
	global_store_dwordx4 v[154:155], v[120:123], off offset:16
	s_nop 1
	s_waitcnt vmcnt(16)
	v_lshlrev_b32_e32 v124, 16, v164
	v_and_b32_e32 v125, 0xffff0000, v164
	v_lshlrev_b32_e32 v120, 16, v165
	v_and_b32_e32 v121, 0xffff0000, v165
	v_lshlrev_b32_e32 v126, 16, v166
	v_and_b32_e32 v127, 0xffff0000, v166
	v_lshlrev_b32_e32 v122, 16, v167
	v_and_b32_e32 v123, 0xffff0000, v167
	v_pk_add_f32 v[118:119], v[118:119], v[120:121]
	v_pk_add_f32 v[116:117], v[116:117], v[124:125]
	v_pk_add_f32 v[114:115], v[114:115], v[122:123]
	v_pk_add_f32 v[112:113], v[112:113], v[126:127]
	global_store_dwordx4 v[154:155], v[116:119], off offset:512
	global_store_dwordx4 v[154:155], v[112:115], off offset:528
.LBB0_243:
	s_or_b64 exec, exec, s[22:23]
	s_nop 0
	v_or_b32_e32 v112, 16, v144
	v_cmp_gt_i32_e32 vcc, s24, v112
	s_and_saveexec_b64 s[22:23], vcc
	s_cbranch_execz .LBB0_245
	v_ashrrev_i32_e32 v113, 31, v112
	v_lshlrev_b64 v[114:115], 11, v[112:113]
	v_lshl_add_u64 v[114:115], s[12:13], 0, v[114:115]
	v_lshl_add_u64 v[114:115], s[20:21], 1, v[114:115]
	v_lshl_add_u64 v[118:119], v[114:115], 0, v[184:185]
	v_lshlrev_b64 v[112:113], 12, v[112:113]
	v_lshl_add_u64 v[112:113], s[10:11], 0, v[112:113]
	v_mov_b32_e32 v143, v185
	v_lshl_add_u64 v[112:113], s[20:21], 2, v[112:113]
	v_lshl_add_u64 v[112:113], v[112:113], 0, v[142:143]
	s_waitcnt vmcnt(17)
	v_lshlrev_b32_e32 v120, 16, v168
	v_and_b32_e32 v121, 0xffff0000, v168
	v_lshlrev_b32_e32 v114, 16, v169
	v_and_b32_e32 v115, 0xffff0000, v169
	v_lshlrev_b32_e32 v122, 16, v170
	v_and_b32_e32 v123, 0xffff0000, v170
	v_lshlrev_b32_e32 v116, 16, v171
	v_and_b32_e32 v117, 0xffff0000, v171
	v_pk_add_f32 v[110:111], v[110:111], v[114:115]
	v_pk_add_f32 v[108:109], v[108:109], v[120:121]
	v_pk_add_f32 v[106:107], v[106:107], v[116:117]
	v_pk_add_f32 v[104:105], v[104:105], v[122:123]
	global_store_dwordx4 v[112:113], v[108:111], off
	global_store_dwordx4 v[112:113], v[104:107], off offset:16
	s_nop 1
	s_waitcnt vmcnt(18)
	v_lshlrev_b32_e32 v108, 16, v172
	v_and_b32_e32 v109, 0xffff0000, v172
	v_lshlrev_b32_e32 v104, 16, v173
	v_and_b32_e32 v105, 0xffff0000, v173
	v_lshlrev_b32_e32 v110, 16, v174
	v_and_b32_e32 v111, 0xffff0000, v174
	v_lshlrev_b32_e32 v106, 16, v175
	v_and_b32_e32 v107, 0xffff0000, v175
	v_pk_add_f32 v[102:103], v[102:103], v[104:105]
	v_pk_add_f32 v[100:101], v[100:101], v[108:109]
	v_pk_add_f32 v[98:99], v[98:99], v[106:107]
	v_pk_add_f32 v[96:97], v[96:97], v[110:111]
	global_store_dwordx4 v[112:113], v[100:103], off offset:512
	global_store_dwordx4 v[112:113], v[96:99], off offset:528
; __device__ __forceinline__ unsigned pk2(float lo, float hi) { f32x2 v = {lo, hi}; bf16x2_hw b = __builtin_convertvector(v, bf16x2_hw); return __builtin_bit_cast(unsigned, b); }
; __device__ __forceinline__ void st_bf8(bf16* p, f32x4 a, f32x4 b) { u32x4 w; w.x = pk2(a[0], a[1]); w.y = pk2(a[2], a[3]); w.z = pk2(b[0], b[1]); w.w = pk2(b[2], b[3]); *(u32x4*)p = w; }
; __device__ __forceinline__ void ld_bf8(const bf16* p, f32x4& a, f32x4& b) { const u32x4 w = *(const u32x4*)p; a = (f32x4){bflo(w.x), bfhi(w.x), bflo(w.y), bfhi(w.y)}; b = (f32x4){bflo(w.z), bfhi(w.z), bflo(w.w), bfhi(w.w)}; }
;     __device__ __forceinline__ void operator()(AccRef acc, const pg8::Unit& u, int wr, int wc, int fr, int fq) const {
;         const int c0 = u.pn * 256;
;         EPI_LOOP_P( if (row < nvalid) { f32x4 b0, b1; ld_bf8(XB + rw * 1024 + c0 + cl, b0, b1); float* p = y + rw * 1024 + c0 + cl; *(f32x4*)p = b0 + v0; *(f32x4*)(p + 4) = b1 + v1; } )
;     }
.LBB0_245:
	s_or_b64 exec, exec, s[22:23]
	s_nop 0
	v_or_b32_e32 v96, 32, v144
	v_cmp_gt_i32_e32 vcc, s24, v96
	s_and_saveexec_b64 s[22:23], vcc
	s_cbranch_execz .LBB0_247
	v_ashrrev_i32_e32 v97, 31, v96
	v_lshlrev_b64 v[98:99], 11, v[96:97]
	v_lshl_add_u64 v[98:99], s[12:13], 0, v[98:99]
	v_lshl_add_u64 v[98:99], s[20:21], 1, v[98:99]
	v_lshl_add_u64 v[102:103], v[98:99], 0, v[184:185]
	v_lshlrev_b64 v[96:97], 12, v[96:97]
	v_lshl_add_u64 v[96:97], s[10:11], 0, v[96:97]
	v_mov_b32_e32 v143, v185
	v_lshl_add_u64 v[96:97], s[20:21], 2, v[96:97]
	v_lshl_add_u64 v[96:97], v[96:97], 0, v[142:143]
	s_waitcnt vmcnt(19)
	v_lshlrev_b32_e32 v104, 16, v176
	v_and_b32_e32 v105, 0xffff0000, v176
	v_lshlrev_b32_e32 v98, 16, v177
	v_and_b32_e32 v99, 0xffff0000, v177
	v_lshlrev_b32_e32 v106, 16, v178
	v_and_b32_e32 v107, 0xffff0000, v178
	v_lshlrev_b32_e32 v100, 16, v179
	v_and_b32_e32 v101, 0xffff0000, v179
	v_pk_add_f32 v[94:95], v[94:95], v[98:99]
	v_pk_add_f32 v[92:93], v[92:93], v[104:105]
	v_pk_add_f32 v[90:91], v[90:91], v[100:101]
	v_pk_add_f32 v[88:89], v[88:89], v[106:107]
	global_store_dwordx4 v[96:97], v[92:95], off
	global_store_dwordx4 v[96:97], v[88:91], off offset:16
	s_nop 1
	s_waitcnt vmcnt(20)
	v_lshlrev_b32_e32 v92, 16, v180
	v_and_b32_e32 v93, 0xffff0000, v180
	v_lshlrev_b32_e32 v88, 16, v181
	v_and_b32_e32 v89, 0xffff0000, v181
	v_lshlrev_b32_e32 v94, 16, v182
	v_and_b32_e32 v95, 0xffff0000, v182
	v_lshlrev_b32_e32 v90, 16, v183
	v_and_b32_e32 v91, 0xffff0000, v183
	v_pk_add_f32 v[86:87], v[86:87], v[88:89]
	v_pk_add_f32 v[84:85], v[84:85], v[92:93]
	v_pk_add_f32 v[82:83], v[82:83], v[90:91]
	v_pk_add_f32 v[80:81], v[80:81], v[94:95]
	global_store_dwordx4 v[96:97], v[84:87], off offset:512
	global_store_dwordx4 v[96:97], v[80:83], off offset:528
.LBB0_247:
	s_or_b64 exec, exec, s[22:23]
	s_nop 0
	v_or_b32_e32 v80, 48, v144
	v_cmp_gt_i32_e32 vcc, s24, v80
	s_and_saveexec_b64 s[22:23], vcc
	s_cbranch_execz .LBB0_249
	v_ashrrev_i32_e32 v81, 31, v80
	v_lshlrev_b64 v[82:83], 11, v[80:81]
	v_lshl_add_u64 v[82:83], s[12:13], 0, v[82:83]
	v_lshl_add_u64 v[82:83], s[20:21], 1, v[82:83]
	v_lshl_add_u64 v[86:87], v[82:83], 0, v[184:185]
	v_lshlrev_b64 v[80:81], 12, v[80:81]
	v_lshl_add_u64 v[80:81], s[10:11], 0, v[80:81]
	v_mov_b32_e32 v143, v185
	v_lshl_add_u64 v[80:81], s[20:21], 2, v[80:81]
	v_lshl_add_u64 v[80:81], v[80:81], 0, v[142:143]
	s_waitcnt vmcnt(21)
	v_lshlrev_b32_e32 v88, 16, v190
	v_and_b32_e32 v89, 0xffff0000, v190
	v_lshlrev_b32_e32 v82, 16, v191
	v_and_b32_e32 v83, 0xffff0000, v191
	v_lshlrev_b32_e32 v90, 16, v192
	v_and_b32_e32 v91, 0xffff0000, v192
	v_lshlrev_b32_e32 v84, 16, v193
	v_and_b32_e32 v85, 0xffff0000, v193
	v_pk_add_f32 v[78:79], v[78:79], v[82:83]
	v_pk_add_f32 v[76:77], v[76:77], v[88:89]
	v_pk_add_f32 v[74:75], v[74:75], v[84:85]
	v_pk_add_f32 v[72:73], v[72:73], v[90:91]
	global_store_dwordx4 v[80:81], v[76:79], off
	global_store_dwordx4 v[80:81], v[72:75], off offset:16
	s_nop 1
	s_waitcnt vmcnt(22)
	v_lshlrev_b32_e32 v76, 16, v196
	v_and_b32_e32 v77, 0xffff0000, v196
	v_lshlrev_b32_e32 v72, 16, v197
	v_and_b32_e32 v73, 0xffff0000, v197
	v_lshlrev_b32_e32 v78, 16, v198
	v_and_b32_e32 v79, 0xffff0000, v198
	v_lshlrev_b32_e32 v74, 16, v199
	v_and_b32_e32 v75, 0xffff0000, v199
	v_pk_add_f32 v[70:71], v[70:71], v[72:73]
	v_pk_add_f32 v[68:69], v[68:69], v[76:77]
	v_pk_add_f32 v[66:67], v[66:67], v[74:75]
	v_pk_add_f32 v[64:65], v[64:65], v[78:79]
	global_store_dwordx4 v[80:81], v[68:71], off offset:512
	global_store_dwordx4 v[80:81], v[64:67], off offset:528
.LBB0_249:
	s_or_b64 exec, exec, s[22:23]
	s_nop 0
	v_add_u32_e32 v64, 0x80, v144
	v_cmp_gt_i32_e32 vcc, s24, v64
	s_and_saveexec_b64 s[22:23], vcc
	s_cbranch_execz .LBB0_251
	v_ashrrev_i32_e32 v65, 31, v64
	v_lshlrev_b64 v[66:67], 11, v[64:65]
	v_lshl_add_u64 v[66:67], s[12:13], 0, v[66:67]
	v_lshl_add_u64 v[66:67], s[20:21], 1, v[66:67]
	v_lshl_add_u64 v[70:71], v[66:67], 0, v[184:185]
	v_lshlrev_b64 v[64:65], 12, v[64:65]
	v_lshl_add_u64 v[64:65], s[10:11], 0, v[64:65]
	v_mov_b32_e32 v143, v185
	v_lshl_add_u64 v[64:65], s[20:21], 2, v[64:65]
	v_lshl_add_u64 v[64:65], v[64:65], 0, v[142:143]
	s_waitcnt vmcnt(23)
	v_lshlrev_b32_e32 v72, 16, v200
	v_and_b32_e32 v73, 0xffff0000, v200
	v_lshlrev_b32_e32 v66, 16, v201
	v_and_b32_e32 v67, 0xffff0000, v201
	v_lshlrev_b32_e32 v74, 16, v202
	v_and_b32_e32 v75, 0xffff0000, v202
	v_lshlrev_b32_e32 v68, 16, v203
	v_and_b32_e32 v69, 0xffff0000, v203
	v_pk_add_f32 v[62:63], v[62:63], v[66:67]
	v_pk_add_f32 v[60:61], v[60:61], v[72:73]
	v_pk_add_f32 v[58:59], v[58:59], v[68:69]
	v_pk_add_f32 v[56:57], v[56:57], v[74:75]
	global_store_dwordx4 v[64:65], v[60:63], off
	global_store_dwordx4 v[64:65], v[56:59], off offset:16
	s_nop 1
	s_waitcnt vmcnt(24)
	v_lshlrev_b32_e32 v60, 16, v212
	v_and_b32_e32 v61, 0xffff0000, v212
	v_lshlrev_b32_e32 v56, 16, v213
	v_and_b32_e32 v57, 0xffff0000, v213
	v_lshlrev_b32_e32 v62, 16, v214
	v_and_b32_e32 v63, 0xffff0000, v214
	v_lshlrev_b32_e32 v58, 16, v215
	v_and_b32_e32 v59, 0xffff0000, v215
	v_pk_add_f32 v[54:55], v[54:55], v[56:57]
	v_pk_add_f32 v[52:53], v[52:53], v[60:61]
	v_pk_add_f32 v[50:51], v[50:51], v[58:59]
	v_pk_add_f32 v[48:49], v[48:49], v[62:63]
	global_store_dwordx4 v[64:65], v[52:55], off offset:512
	global_store_dwordx4 v[64:65], v[48:51], off offset:528
; __device__ __forceinline__ unsigned pk2(float lo, float hi) { f32x2 v = {lo, hi}; bf16x2_hw b = __builtin_convertvector(v, bf16x2_hw); return __builtin_bit_cast(unsigned, b); }
; __device__ __forceinline__ void st_bf8(bf16* p, f32x4 a, f32x4 b) { u32x4 w; w.x = pk2(a[0], a[1]); w.y = pk2(a[2], a[3]); w.z = pk2(b[0], b[1]); w.w = pk2(b[2], b[3]); *(u32x4*)p = w; }
; __device__ __forceinline__ void ld_bf8(const bf16* p, f32x4& a, f32x4& b) { const u32x4 w = *(const u32x4*)p; a = (f32x4){bflo(w.x), bfhi(w.x), bflo(w.y), bfhi(w.y)}; b = (f32x4){bflo(w.z), bfhi(w.z), bflo(w.w), bfhi(w.w)}; }
;     __device__ __forceinline__ void operator()(AccRef acc, const pg8::Unit& u, int wr, int wc, int fr, int fq) const {
;         const int c0 = u.pn * 256;
;         EPI_LOOP_P( if (row < nvalid) { f32x4 b0, b1; ld_bf8(XB + rw * 1024 + c0 + cl, b0, b1); float* p = y + rw * 1024 + c0 + cl; *(f32x4*)p = b0 + v0; *(f32x4*)(p + 4) = b1 + v1; } )
;     }
.LBB0_251:
	s_or_b64 exec, exec, s[22:23]
	s_nop 0
	v_add_u32_e32 v48, 0x90, v144
	v_cmp_gt_i32_e32 vcc, s24, v48
	s_and_saveexec_b64 s[22:23], vcc
	s_cbranch_execz .LBB0_253
	v_ashrrev_i32_e32 v49, 31, v48
	v_lshlrev_b64 v[50:51], 11, v[48:49]
	v_lshl_add_u64 v[50:51], s[12:13], 0, v[50:51]
	v_lshl_add_u64 v[50:51], s[20:21], 1, v[50:51]
	v_lshl_add_u64 v[54:55], v[50:51], 0, v[184:185]
	v_lshlrev_b64 v[48:49], 12, v[48:49]
	v_lshl_add_u64 v[48:49], s[10:11], 0, v[48:49]
	v_mov_b32_e32 v143, v185
	v_lshl_add_u64 v[48:49], s[20:21], 2, v[48:49]
	v_lshl_add_u64 v[48:49], v[48:49], 0, v[142:143]
	s_waitcnt vmcnt(25)
	v_lshlrev_b32_e32 v56, 16, v216
	v_and_b32_e32 v57, 0xffff0000, v216
	v_lshlrev_b32_e32 v50, 16, v217
	v_and_b32_e32 v51, 0xffff0000, v217
	v_lshlrev_b32_e32 v58, 16, v218
	v_and_b32_e32 v59, 0xffff0000, v218
	v_lshlrev_b32_e32 v52, 16, v219
	v_and_b32_e32 v53, 0xffff0000, v219
	v_pk_add_f32 v[46:47], v[46:47], v[50:51]
	v_pk_add_f32 v[44:45], v[44:45], v[56:57]
	v_pk_add_f32 v[42:43], v[42:43], v[52:53]
	v_pk_add_f32 v[40:41], v[40:41], v[58:59]
	global_store_dwordx4 v[48:49], v[44:47], off
	global_store_dwordx4 v[48:49], v[40:43], off offset:16
	s_nop 1
	s_waitcnt vmcnt(26)
	v_lshlrev_b32_e32 v44, 16, v220
	v_and_b32_e32 v45, 0xffff0000, v220
	v_lshlrev_b32_e32 v40, 16, v221
	v_and_b32_e32 v41, 0xffff0000, v221
	v_lshlrev_b32_e32 v46, 16, v222
	v_and_b32_e32 v47, 0xffff0000, v222
	v_lshlrev_b32_e32 v42, 16, v223
	v_and_b32_e32 v43, 0xffff0000, v223
	v_pk_add_f32 v[38:39], v[38:39], v[40:41]
	v_pk_add_f32 v[36:37], v[36:37], v[44:45]
	v_pk_add_f32 v[34:35], v[34:35], v[42:43]
	v_pk_add_f32 v[32:33], v[32:33], v[46:47]
	global_store_dwordx4 v[48:49], v[36:39], off offset:512
	global_store_dwordx4 v[48:49], v[32:35], off offset:528
.LBB0_253:
	s_or_b64 exec, exec, s[22:23]
	s_nop 0
	v_add_u32_e32 v32, 0xa0, v144
	v_cmp_gt_i32_e32 vcc, s24, v32
	s_and_saveexec_b64 s[22:23], vcc
	s_cbranch_execz .LBB0_255
	v_ashrrev_i32_e32 v33, 31, v32
	v_lshlrev_b64 v[34:35], 11, v[32:33]
	v_lshl_add_u64 v[34:35], s[12:13], 0, v[34:35]
	v_lshl_add_u64 v[34:35], s[20:21], 1, v[34:35]
	v_lshl_add_u64 v[38:39], v[34:35], 0, v[184:185]
	v_lshlrev_b64 v[32:33], 12, v[32:33]
	v_lshl_add_u64 v[32:33], s[10:11], 0, v[32:33]
	v_mov_b32_e32 v143, v185
	v_lshl_add_u64 v[32:33], s[20:21], 2, v[32:33]
	v_lshl_add_u64 v[32:33], v[32:33], 0, v[142:143]
	s_waitcnt vmcnt(27)
	v_lshlrev_b32_e32 v40, 16, v224
	v_and_b32_e32 v41, 0xffff0000, v224
	v_lshlrev_b32_e32 v34, 16, v225
	v_and_b32_e32 v35, 0xffff0000, v225
	v_lshlrev_b32_e32 v42, 16, v226
	v_and_b32_e32 v43, 0xffff0000, v226
	v_lshlrev_b32_e32 v36, 16, v227
	v_and_b32_e32 v37, 0xffff0000, v227
	v_pk_add_f32 v[30:31], v[30:31], v[34:35]
	v_pk_add_f32 v[28:29], v[28:29], v[40:41]
	v_pk_add_f32 v[26:27], v[26:27], v[36:37]
	v_pk_add_f32 v[24:25], v[24:25], v[42:43]
	global_store_dwordx4 v[32:33], v[28:31], off
	global_store_dwordx4 v[32:33], v[24:27], off offset:16
	s_nop 1
	s_waitcnt vmcnt(28)
	v_lshlrev_b32_e32 v28, 16, v228
	v_and_b32_e32 v29, 0xffff0000, v228
	v_lshlrev_b32_e32 v24, 16, v229
	v_and_b32_e32 v25, 0xffff0000, v229
	v_lshlrev_b32_e32 v30, 16, v230
	v_and_b32_e32 v31, 0xffff0000, v230
	v_lshlrev_b32_e32 v26, 16, v231
	v_and_b32_e32 v27, 0xffff0000, v231
	v_pk_add_f32 v[22:23], v[22:23], v[24:25]
	v_pk_add_f32 v[20:21], v[20:21], v[28:29]
	v_pk_add_f32 v[18:19], v[18:19], v[26:27]
	v_pk_add_f32 v[16:17], v[16:17], v[30:31]
	global_store_dwordx4 v[32:33], v[20:23], off offset:512
	global_store_dwordx4 v[32:33], v[16:19], off offset:528
.LBB0_255:
	s_or_b64 exec, exec, s[22:23]
	s_nop 0
	v_add_u32_e32 v16, 0xb0, v144
	v_cmp_gt_i32_e32 vcc, s24, v16
	s_and_saveexec_b64 s[22:23], vcc
	s_cbranch_execz .LBB0_257
	v_ashrrev_i32_e32 v17, 31, v16
	v_lshlrev_b64 v[18:19], 11, v[16:17]
	v_lshl_add_u64 v[18:19], s[12:13], 0, v[18:19]
	v_lshl_add_u64 v[18:19], s[20:21], 1, v[18:19]
	v_lshl_add_u64 v[22:23], v[18:19], 0, v[184:185]
	v_lshlrev_b64 v[16:17], 12, v[16:17]
	v_lshl_add_u64 v[16:17], s[10:11], 0, v[16:17]
	v_mov_b32_e32 v143, v185
	v_lshl_add_u64 v[16:17], s[20:21], 2, v[16:17]
	v_lshl_add_u64 v[16:17], v[16:17], 0, v[142:143]
	s_waitcnt vmcnt(29)
	v_lshlrev_b32_e32 v24, 16, v232
	v_and_b32_e32 v25, 0xffff0000, v232
	v_lshlrev_b32_e32 v18, 16, v233
	v_and_b32_e32 v19, 0xffff0000, v233
	v_lshlrev_b32_e32 v26, 16, v234
	v_and_b32_e32 v27, 0xffff0000, v234
	v_lshlrev_b32_e32 v20, 16, v235
	v_and_b32_e32 v21, 0xffff0000, v235
	v_pk_add_f32 v[14:15], v[14:15], v[18:19]
	v_pk_add_f32 v[12:13], v[12:13], v[24:25]
	v_pk_add_f32 v[10:11], v[10:11], v[20:21]
	v_pk_add_f32 v[8:9], v[8:9], v[26:27]
	global_store_dwordx4 v[16:17], v[12:15], off
	global_store_dwordx4 v[16:17], v[8:11], off offset:16
	s_nop 1
	s_waitcnt vmcnt(30)
	v_lshlrev_b32_e32 v12, 16, v236
	v_and_b32_e32 v13, 0xffff0000, v236
	v_lshlrev_b32_e32 v8, 16, v237
	v_and_b32_e32 v9, 0xffff0000, v237
	v_lshlrev_b32_e32 v14, 16, v238
	v_and_b32_e32 v15, 0xffff0000, v238
	v_lshlrev_b32_e32 v10, 16, v239
	v_and_b32_e32 v11, 0xffff0000, v239
	v_pk_add_f32 v[6:7], v[6:7], v[8:9]
	v_pk_add_f32 v[4:5], v[4:5], v[12:13]
	v_pk_add_f32 v[2:3], v[2:3], v[10:11]
	v_pk_add_f32 v[0:1], v[0:1], v[14:15]
	global_store_dwordx4 v[16:17], v[4:7], off offset:512
	global_store_dwordx4 v[16:17], v[0:3], off offset:528
